# attention rescale test: redundant self-canonicalising v_max ops removed from the per-tile max chain (MLA 4, DF 2 per tile)
# speedup vs baseline: 1.0111x; 1.0014x over previous
; #define PIN() do { asm volatile("" ::: "memory"); __builtin_amdgcn_sched_barrier(0); } while (0)
; #define GLOAD(kt_) do { const bf16_t* kp_ = Kb + (size_t)(kt_) * 64 * DQK; const bf16_t* vp_ = VTb + (kt_) * 64; \
;     kreg0 = *(const uint4*)(kp_ + kgo[0]); kreg1 = *(const uint4*)(kp_ + kgo[1]); if (NKC > 2) kreg2 = *(const uint4*)(kp_ + kgo[2]); \
;     vreg0 = *(const uint4*)(vp_ + vgo0); vreg1 = *(const uint4*)(vp_ + vgo1); } while (0)
; #define KLD(dst_, s_) do { dst_[0] = *(const bf16x8*)(kbase + (s_) * 32); dst_[1] = *(const bf16x8*)(kbase + 32 * KSTR + (s_) * 32); \
;         dst_[2] = *(const bf16x8*)(kbase + ((s_) + 1) * 32); dst_[3] = *(const bf16x8*)(kbase + 32 * KSTR + ((s_) + 1) * 32); } while (0)
; #define KMM(src_, s_) do { sacc[0] = MFMA(src_[0], qf[s_], sacc[0]); sacc[1] = MFMA(src_[1], qf[s_], sacc[1]); \
;         sacc[0] = MFMA(src_[2], qf[(s_) + 1], sacc[0]); sacc[1] = MFMA(src_[3], qf[(s_) + 1], sacc[1]); } while (0)
; template <int DQK, int NM>
; DI void attn_item(const bf16_t* Qb, const bf16_t* Kb, size_t mstride, const bf16_t* VTb,
;                   int q0, int nkt, float cs, bf16_t* Orow  , float lam, float outscale, const float* subw, char* smem) {
;     ...
;   for (int kt = 0; kt < nkt; ++kt) {
;     const char* cur = smem + (kt & 1) * BUF;
;     GLOAD(kt + 1 < nkt ? kt + 1 : kt);
;     PIN();
;     f32x16 sacc[2];
; #pragma unroll
;     for (int kb = 0; kb < 2; ++kb)
; #pragma unroll
;       for (int i = 0; i < 16; ++i) sacc[kb][i] = 0.f;
;     const char* kbase = cur + (m * 64 + l31) * KSTR + hh * 16;
;     {
;       bf16x8 kfa[4], kfb[4];
;     ...
;       KLD(kfa, 0);
; #pragma unroll
;       for (int g = 0; g < NS / 2; ++g) {
;         PIN();
;         if (g + 1 < NS / 2) { if (g & 1) KLD(kfa, 2 * g + 2); else KLD(kfb, 2 * g + 2); }
;         PIN();
;         if (g & 1) KMM(kfb, 2 * g); else KMM(kfa, 2 * g);
;       }
;     ...
;     }
;     float mx = sacc[0][0];
; #pragma unroll
;     for (int i = 1; i < 16; ++i) mx = fmaxf(mx, sacc[0][i]);
; #pragma unroll
;     for (int i = 0; i < 16; ++i) mx = fmaxf(mx, sacc[1][i]);
;     {
;       const auto rr = __builtin_amdgcn_permlane32_swap(__float_as_uint(mx), __float_as_uint(mx), false, false);
;       mx = fmaxf(__uint_as_float(rr[0]), __uint_as_float(rr[1]));
;     }
;     if (__any((mx - mrun) * cs > 8.f)) {
.LBB0_127:
	v_lshl_add_u64 v[64:65], s[20:21], 0, v[190:191]
	v_lshl_add_u64 v[66:67], s[20:21], 0, v[192:193]
	global_load_dwordx4 v[158:161], v[64:65], off
	global_load_dwordx4 v[154:157], v[66:67], off
	v_lshl_add_u64 v[64:65], s[20:21], 0, v[194:195]
	s_mov_b32 s24, 0xca06000
	v_add_co_u32_e32 v64, vcc, s24, v64
	v_lshl_add_u64 v[66:67], s[20:21], 0, v[186:187]
	s_nop 0
	v_addc_co_u32_e32 v65, vcc, 0, v65, vcc
	global_load_dwordx4 v[162:165], v[64:65], off
	global_load_dwordx4 v[150:153], v[66:67], off
	v_lshl_add_u64 v[64:65], s[20:21], 0, v[188:189]
	global_load_dwordx4 v[146:149], v[64:65], off
	s_and_b32 s24, 1, s37
	s_cselect_b32 s25, 0, 0xac00
	s_add_i32 s25, s25, 0
	v_add3_u32 v196, s25, v217, v170
	ds_read_b128 v[64:67], v196
	ds_read_b128 v[220:223], v196 offset:32
	ds_read_b128 v[68:71], v196 offset:12800
	ds_read_b128 v[224:227], v196 offset:12832
	ds_read_b128 v[228:231], v196 offset:64
	ds_read_b128 v[232:235], v196 offset:96
	ds_read_b128 v[236:239], v196 offset:12864
	ds_read_b128 v[240:243], v196 offset:12896
	s_waitcnt lgkmcnt(7)
	v_mfma_f32_32x32x16_bf16 v[80:95], v[64:67], v[142:145], 0
	s_waitcnt lgkmcnt(5)
	v_mfma_f32_32x32x16_bf16 v[64:79], v[68:71], v[142:145], 0
	v_mfma_f32_32x32x16_bf16 v[80:95], v[220:223], v[136:139], v[80:95]
	s_waitcnt lgkmcnt(4)
	v_mfma_f32_32x32x16_bf16 v[64:79], v[224:227], v[136:139], v[64:79]
	ds_read_b128 v[220:223], v196 offset:128
	ds_read_b128 v[224:227], v196 offset:160
	ds_read_b128 v[244:247], v196 offset:12928
	ds_read_b128 v[248:251], v196 offset:12960
	s_waitcnt lgkmcnt(7)
	v_mfma_f32_32x32x16_bf16 v[80:95], v[228:231], v[132:135], v[80:95]
	s_waitcnt lgkmcnt(5)
	v_mfma_f32_32x32x16_bf16 v[64:79], v[236:239], v[132:135], v[64:79]
	v_mfma_f32_32x32x16_bf16 v[80:95], v[232:235], v[128:131], v[80:95]
	s_waitcnt lgkmcnt(4)
	v_mfma_f32_32x32x16_bf16 v[64:79], v[240:243], v[128:131], v[64:79]
	ds_read_b128 v[228:231], v196 offset:192
	ds_read_b128 v[232:235], v196 offset:224
	ds_read_b128 v[236:239], v196 offset:12992
	ds_read_b128 v[240:243], v196 offset:13024
	s_waitcnt lgkmcnt(7)
	v_mfma_f32_32x32x16_bf16 v[80:95], v[220:223], v[124:127], v[80:95]
	s_waitcnt lgkmcnt(5)
	v_mfma_f32_32x32x16_bf16 v[64:79], v[244:247], v[124:127], v[64:79]
	v_mfma_f32_32x32x16_bf16 v[80:95], v[224:227], v[120:123], v[80:95]
	s_waitcnt lgkmcnt(4)
	v_mfma_f32_32x32x16_bf16 v[64:79], v[248:251], v[120:123], v[64:79]
	ds_read_b128 v[220:223], v196 offset:256
	ds_read_b128 v[224:227], v196 offset:288
	ds_read_b128 v[244:247], v196 offset:13056
	ds_read_b128 v[248:251], v196 offset:13088
	s_waitcnt lgkmcnt(7)
	v_mfma_f32_32x32x16_bf16 v[80:95], v[228:231], v[116:119], v[80:95]
	s_waitcnt lgkmcnt(5)
	v_mfma_f32_32x32x16_bf16 v[64:79], v[236:239], v[116:119], v[64:79]
	v_mfma_f32_32x32x16_bf16 v[80:95], v[232:235], v[112:115], v[80:95]
	s_waitcnt lgkmcnt(4)
	v_mfma_f32_32x32x16_bf16 v[64:79], v[240:243], v[112:115], v[64:79]
	ds_read_b128 v[228:231], v196 offset:320
	ds_read_b128 v[232:235], v196 offset:352
	ds_read_b128 v[236:239], v196 offset:13120
	ds_read_b128 v[240:243], v196 offset:13152
	s_waitcnt lgkmcnt(7)
	v_mfma_f32_32x32x16_bf16 v[80:95], v[220:223], v[108:111], v[80:95]
	s_waitcnt lgkmcnt(5)
	v_mfma_f32_32x32x16_bf16 v[64:79], v[244:247], v[108:111], v[64:79]
	v_mfma_f32_32x32x16_bf16 v[80:95], v[224:227], v[104:107], v[80:95]
	s_waitcnt lgkmcnt(4)
	v_mfma_f32_32x32x16_bf16 v[64:79], v[248:251], v[104:107], v[64:79]
	s_waitcnt lgkmcnt(3)
	v_mfma_f32_32x32x16_bf16 v[80:95], v[228:231], v[100:103], v[80:95]
	s_waitcnt lgkmcnt(2)
	v_mfma_f32_32x32x16_bf16 v[80:95], v[232:235], v[96:99], v[80:95]
	s_waitcnt lgkmcnt(1)
	v_mfma_f32_32x32x16_bf16 v[64:79], v[236:239], v[100:103], v[64:79]
	s_mov_b64 s[34:35], 0x80
	s_add_i32 s37, s37, 1
	v_lshl_add_u64 v[186:187], v[186:187], 0, s[34:35]
	v_lshl_add_u64 v[188:189], v[188:189], 0, s[34:35]
	s_mov_b64 s[34:35], 0x6000
	v_lshl_add_u64 v[190:191], v[190:191], 0, s[34:35]
	v_lshl_add_u64 v[192:193], v[192:193], 0, s[34:35]
	v_lshl_add_u64 v[194:195], v[194:195], 0, s[34:35]
	s_nop 1
	v_max_f32_e32 v196, v80, v81
	v_max3_f32 v196, v196, v82, v83
	v_max3_f32 v196, v196, v84, v85
	v_max3_f32 v196, v196, v86, v87
	v_max3_f32 v196, v196, v88, v89
	s_waitcnt lgkmcnt(0)
	v_mfma_f32_32x32x16_bf16 v[64:79], v[240:243], v[96:99], v[64:79]
	v_max3_f32 v196, v196, v90, v91
	v_max3_f32 v196, v196, v92, v93
	v_max3_f32 v196, v196, v94, v95
	s_cmp_eq_u32 s24, 1
	s_cselect_b32 s24, 0xac00, 0
	v_add_u32_e32 v206, s24, v197
	v_add_u32_e32 v211, s24, v216
	s_nop 4
	v_max3_f32 v196, v196, v64, v65
	v_max3_f32 v196, v196, v66, v67
	v_max3_f32 v196, v196, v68, v69
	v_max3_f32 v196, v196, v70, v71
	v_max3_f32 v196, v196, v72, v73
	v_max3_f32 v196, v196, v74, v75
	v_max3_f32 v196, v196, v76, v77
	v_max3_f32 v196, v196, v78, v79
	v_mov_b32_e32 v219, v196
	s_nop 1
	v_permlane32_swap_b32_e32 v196, v219
	v_max_f32_e32 v196, v196, v219
	v_sub_f32_e32 v219, v196, v218
	v_mul_f32_e32 v219, 0x3dd53b95, v219
	v_cmp_lt_f32_e32 vcc, s5, v219
	s_cbranch_vccz .LBB0_126
; template <int DQK, int NM>
; DI void attn_item(const bf16_t* Qb, const bf16_t* Kb, size_t mstride, const bf16_t* VTb,
;                   int q0, int nkt, float cs, bf16_t* Orow  , float lam, float outscale, const float* subw, char* smem) {
;     ...
;     if (__any((mx - mrun) * cs > 8.f)) {
;       const float mnew = fmaxf(mrun, mx);
;       const float alpha = __builtin_amdgcn_exp2f((mrun - mnew) * cs);
;       mrun = mnew;
;       lrun *= alpha;
; #pragma unroll
;       for (int db = 0; db < 4; ++db)
; #pragma unroll
;         for (int i = 0; i < 16; ++i) oacc[db][i] *= alpha;
;     }
	v_max_f32_e32 v196, v196, v196
	v_max_f32_e32 v219, v218, v218
	v_max_f32_e32 v219, v219, v196
	v_sub_f32_e32 v196, v218, v219
	v_mul_f32_e32 v196, 0x3dd53b95, v196
	v_exp_f32_e32 v196, v196
	v_mov_b32_e32 v218, v219
	v_pk_mul_f32 v[46:47], v[46:47], v[196:197] op_sel_hi:[1,0]
	v_pk_mul_f32 v[44:45], v[44:45], v[196:197] op_sel_hi:[1,0]
	v_pk_mul_f32 v[42:43], v[42:43], v[196:197] op_sel_hi:[1,0]
	v_pk_mul_f32 v[40:41], v[40:41], v[196:197] op_sel_hi:[1,0]
	v_pk_mul_f32 v[38:39], v[38:39], v[196:197] op_sel_hi:[1,0]
	v_pk_mul_f32 v[36:37], v[36:37], v[196:197] op_sel_hi:[1,0]
	v_pk_mul_f32 v[34:35], v[34:35], v[196:197] op_sel_hi:[1,0]
	v_pk_mul_f32 v[32:33], v[32:33], v[196:197] op_sel_hi:[1,0]
	v_pk_mul_f32 v[62:63], v[62:63], v[196:197] op_sel_hi:[1,0]
	v_pk_mul_f32 v[60:61], v[60:61], v[196:197] op_sel_hi:[1,0]
	v_pk_mul_f32 v[58:59], v[58:59], v[196:197] op_sel_hi:[1,0]
	v_pk_mul_f32 v[56:57], v[56:57], v[196:197] op_sel_hi:[1,0]
	v_pk_mul_f32 v[54:55], v[54:55], v[196:197] op_sel_hi:[1,0]
	v_pk_mul_f32 v[52:53], v[52:53], v[196:197] op_sel_hi:[1,0]
	v_pk_mul_f32 v[50:51], v[50:51], v[196:197] op_sel_hi:[1,0]
	v_pk_mul_f32 v[48:49], v[48:49], v[196:197] op_sel_hi:[1,0]
	v_pk_mul_f32 v[30:31], v[30:31], v[196:197] op_sel_hi:[1,0]
	v_pk_mul_f32 v[28:29], v[28:29], v[196:197] op_sel_hi:[1,0]
	v_pk_mul_f32 v[26:27], v[26:27], v[196:197] op_sel_hi:[1,0]
	v_pk_mul_f32 v[24:25], v[24:25], v[196:197] op_sel_hi:[1,0]
	v_pk_mul_f32 v[22:23], v[22:23], v[196:197] op_sel_hi:[1,0]
	v_pk_mul_f32 v[20:21], v[20:21], v[196:197] op_sel_hi:[1,0]
	v_pk_mul_f32 v[18:19], v[18:19], v[196:197] op_sel_hi:[1,0]
	v_pk_mul_f32 v[16:17], v[16:17], v[196:197] op_sel_hi:[1,0]
	v_pk_mul_f32 v[14:15], v[14:15], v[196:197] op_sel_hi:[1,0]
	v_pk_mul_f32 v[12:13], v[12:13], v[196:197] op_sel_hi:[1,0]
	v_pk_mul_f32 v[10:11], v[10:11], v[196:197] op_sel_hi:[1,0]
	v_pk_mul_f32 v[8:9], v[8:9], v[196:197] op_sel_hi:[1,0]
	v_pk_mul_f32 v[6:7], v[6:7], v[196:197] op_sel_hi:[1,0]
	v_pk_mul_f32 v[4:5], v[4:5], v[196:197] op_sel_hi:[1,0]
	v_pk_mul_f32 v[2:3], v[2:3], v[196:197] op_sel_hi:[1,0]
	v_pk_mul_f32 v[0:1], v[0:1], v[196:197] op_sel_hi:[1,0]
	v_mul_f32_e32 v185, v185, v196
	s_branch .LBB0_126

.LBB0_258:
	v_lshl_add_u64 v[194:195], v[186:187], 0, s[0:1]
	v_add_co_u32_e32 v96, vcc, 0xa904000, v194
	v_lshl_add_u64 v[192:193], v[188:189], 0, s[0:1]
	s_nop 0
	v_addc_co_u32_e32 v97, vcc, 0, v195, vcc
	global_load_dwordx4 v[158:161], v[96:97], off
	v_add_co_u32_e32 v96, vcc, 0xa904000, v192
	s_mov_b32 s24, 0xeb00000
	s_nop 0
	v_addc_co_u32_e32 v97, vcc, 0, v193, vcc
	global_load_dwordx4 v[154:157], v[96:97], off
	v_lshl_add_u64 v[96:97], v[182:183], 0, s[0:1]
	v_add_co_u32_e32 v196, vcc, s24, v96
	s_nop 1
	v_addc_co_u32_e32 v197, vcc, 0, v97, vcc
	v_lshl_add_u64 v[96:97], v[184:185], 0, s[0:1]
	v_add_co_u32_e32 v198, vcc, s24, v96
	global_load_dwordx4 v[150:153], v[196:197], off offset:256
	s_nop 0
	v_addc_co_u32_e32 v199, vcc, 0, v97, vcc
	global_load_dwordx4 v[146:149], v[198:199], off offset:256
	ds_read_b128 v[96:99], v219 offset:18432
	ds_read_b128 v[222:225], v219 offset:18464
	ds_read_b128 v[100:103], v219 offset:23040
	ds_read_b128 v[226:229], v219 offset:23072
	ds_read_b128 v[230:233], v219 offset:18496
	ds_read_b128 v[234:237], v219 offset:18528
	ds_read_b128 v[238:241], v219 offset:23104
	ds_read_b128 v[242:245], v219 offset:23136
	v_mul_f32_e32 v190, 0x3e38aa3b, v220
	s_waitcnt lgkmcnt(7)
	v_mfma_f32_32x32x16_bf16 v[112:127], v[96:99], v[142:145], 0
	v_fma_f32 v80, v80, s78, -v190
	v_fma_f32 v81, v81, s78, -v190
	v_fma_f32 v82, v82, s78, -v190
	v_fma_f32 v83, v83, s78, -v190
	v_exp_f32_e32 v80, v80
	v_exp_f32_e32 v81, v81
	v_exp_f32_e32 v82, v82
	v_exp_f32_e32 v83, v83
	v_pk_add_f32 v[96:97], v[80:81], 0 op_sel_hi:[1,0]
	v_cvt_pk_bf16_f32 v80, v80, v81
	v_pk_add_f32 v[246:247], v[82:83], v[96:97]
	v_cvt_pk_bf16_f32 v81, v82, v83
	s_waitcnt lgkmcnt(5)
	v_mfma_f32_32x32x16_bf16 v[96:111], v[100:103], v[142:145], 0
	v_mfma_f32_32x32x16_bf16 v[112:127], v[222:225], v[136:139], v[112:127]
	v_fma_f32 v82, v84, s78, -v190
	v_fma_f32 v83, v85, s78, -v190
	v_fma_f32 v84, v86, s78, -v190
	v_fma_f32 v85, v87, s78, -v190
	v_exp_f32_e32 v82, v82
	v_exp_f32_e32 v83, v83
	v_exp_f32_e32 v84, v84
	v_exp_f32_e32 v85, v85
	v_pk_add_f32 v[86:87], v[82:83], v[246:247]
	v_cvt_pk_bf16_f32 v82, v82, v83
	v_pk_add_f32 v[86:87], v[84:85], v[86:87]
	v_cvt_pk_bf16_f32 v83, v84, v85
	s_waitcnt lgkmcnt(4)
	v_mfma_f32_32x32x16_bf16 v[96:111], v[226:229], v[136:139], v[96:111]
	s_waitcnt lgkmcnt(3)
	v_mfma_f32_32x32x16_bf16 v[112:127], v[230:233], v[132:135], v[112:127]
	v_fma_f32 v84, v88, s78, -v190
	v_fma_f32 v85, v89, s78, -v190
	v_fma_f32 v88, v90, s78, -v190
	v_fma_f32 v89, v91, s78, -v190
	v_exp_f32_e32 v84, v84
	v_exp_f32_e32 v85, v85
	v_exp_f32_e32 v88, v88
	v_exp_f32_e32 v89, v89
	v_pk_add_f32 v[86:87], v[84:85], v[86:87]
	v_cvt_pk_bf16_f32 v84, v84, v85
	v_pk_add_f32 v[86:87], v[88:89], v[86:87]
	v_cvt_pk_bf16_f32 v85, v88, v89
	s_waitcnt lgkmcnt(1)
	v_mfma_f32_32x32x16_bf16 v[96:111], v[238:241], v[132:135], v[96:111]
	v_mfma_f32_32x32x16_bf16 v[112:127], v[234:237], v[128:131], v[112:127]
	v_fma_f32 v88, v92, s78, -v190
	v_fma_f32 v89, v93, s78, -v190
	v_fma_f32 v90, v94, s78, -v190
	v_fma_f32 v91, v95, s78, -v190
	v_exp_f32_e32 v88, v88
	v_exp_f32_e32 v89, v89
	v_exp_f32_e32 v90, v90
	v_exp_f32_e32 v91, v91
	v_pk_add_f32 v[86:87], v[88:89], v[86:87]
	s_nop 0
	v_pk_add_f32 v[246:247], v[90:91], v[86:87]
	v_cvt_pk_bf16_f32 v86, v88, v89
	v_cvt_pk_bf16_f32 v87, v90, v91
	s_waitcnt lgkmcnt(0)
	v_mfma_f32_32x32x16_bf16 v[96:111], v[242:245], v[128:131], v[96:111]
	s_mul_i32 s27, s30, 0x4800
	s_add_i32 s24, s30, 1
	v_add_u32_e32 v221, s27, v218
	s_cmp_lg_u32 s30, 2
	ds_read_b128 v[88:91], v221 offset:36864
	ds_read_b128 v[92:95], v221 offset:41472
	ds_read_b128 v[222:225], v221 offset:46080
	ds_read_b128 v[226:229], v221 offset:50688
	s_cselect_b32 s24, s24, 0
	s_add_i32 s25, s24, 1
	s_cmp_lg_u32 s24, 2
	s_cselect_b32 s30, s25, 0
	s_mul_i32 s25, s30, 0x4800
	s_add_i32 s27, s25, 0
	v_add_u32_e32 v248, s27, v180
	v_add_u32_e32 v249, s27, v178
	ds_read_b128 v[230:233], v221 offset:36896
	ds_read_b128 v[234:237], v221 offset:41504
	ds_read_b128 v[238:241], v221 offset:46112
	ds_read_b128 v[242:245], v221 offset:50720
	s_waitcnt lgkmcnt(7)
	v_mfma_f32_32x32x16_bf16 v[16:31], v[88:91], v[80:83], v[16:31]
	v_fma_f32 v64, v64, s78, -v190
	v_fma_f32 v65, v65, s78, -v190
	v_fma_f32 v66, v66, s78, -v190
	v_fma_f32 v67, v67, s78, -v190
	v_exp_f32_e32 v64, v64
	v_exp_f32_e32 v65, v65
	v_exp_f32_e32 v66, v66
	v_exp_f32_e32 v67, v67
	v_pk_add_f32 v[88:89], v[64:65], v[246:247]
	v_cvt_pk_bf16_f32 v64, v64, v65
	v_pk_add_f32 v[88:89], v[66:67], v[88:89]
	v_cvt_pk_bf16_f32 v65, v66, v67
	s_waitcnt lgkmcnt(6)
	v_mfma_f32_32x32x16_bf16 v[48:63], v[92:95], v[80:83], v[48:63]
	s_waitcnt lgkmcnt(5)
	v_mfma_f32_32x32x16_bf16 v[32:47], v[222:225], v[80:83], v[32:47]
	v_fma_f32 v66, v68, s78, -v190
	v_fma_f32 v67, v69, s78, -v190
	v_fma_f32 v68, v70, s78, -v190
	v_fma_f32 v69, v71, s78, -v190
	v_exp_f32_e32 v66, v66
	v_exp_f32_e32 v67, v67
	v_exp_f32_e32 v68, v68
	v_exp_f32_e32 v69, v69
	v_pk_add_f32 v[70:71], v[66:67], v[88:89]
	v_cvt_pk_bf16_f32 v66, v66, v67
	v_pk_add_f32 v[222:223], v[68:69], v[70:71]
	v_cvt_pk_bf16_f32 v67, v68, v69
	s_waitcnt lgkmcnt(4)
	v_mfma_f32_32x32x16_bf16 v[0:15], v[226:229], v[80:83], v[0:15]
	s_waitcnt vmcnt(3)
	ds_write_b128 v217, v[158:161]
	ds_read_b128 v[68:71], v221 offset:36928
	ds_read_b128 v[80:83], v221 offset:41536
	ds_read_b128 v[88:91], v221 offset:46144
	ds_read_b128 v[92:95], v221 offset:50752
	s_waitcnt lgkmcnt(8)
	v_mfma_f32_32x32x16_bf16 v[16:31], v[230:233], v[84:87], v[16:31]
	v_fma_f32 v72, v72, s78, -v190
	v_fma_f32 v73, v73, s78, -v190
	v_fma_f32 v74, v74, s78, -v190
	v_fma_f32 v75, v75, s78, -v190
	v_exp_f32_e32 v72, v72
	v_exp_f32_e32 v73, v73
	v_exp_f32_e32 v74, v74
	v_exp_f32_e32 v75, v75
	v_pk_add_f32 v[158:159], v[72:73], v[222:223]
	v_cvt_pk_bf16_f32 v72, v72, v73
	v_pk_add_f32 v[158:159], v[74:75], v[158:159]
	v_cvt_pk_bf16_f32 v73, v74, v75
	s_waitcnt lgkmcnt(7)
	v_mfma_f32_32x32x16_bf16 v[48:63], v[234:237], v[84:87], v[48:63]
	s_waitcnt lgkmcnt(6)
	v_mfma_f32_32x32x16_bf16 v[32:47], v[238:241], v[84:87], v[32:47]
	v_fma_f32 v74, v76, s78, -v190
	v_fma_f32 v75, v77, s78, -v190
	v_fma_f32 v76, v78, s78, -v190
	v_fma_f32 v77, v79, s78, -v190
	v_exp_f32_e32 v74, v74
	v_exp_f32_e32 v75, v75
	v_exp_f32_e32 v76, v76
	v_exp_f32_e32 v77, v77
	v_pk_add_f32 v[78:79], v[74:75], v[158:159]
	v_cvt_pk_bf16_f32 v74, v74, v75
	v_pk_add_f32 v[222:223], v[76:77], v[78:79]
	v_cvt_pk_bf16_f32 v75, v76, v77
	s_waitcnt lgkmcnt(5)
	v_mfma_f32_32x32x16_bf16 v[0:15], v[242:245], v[84:87], v[0:15]
	s_waitcnt vmcnt(2)
	ds_write_b128 v216, v[154:157]
	ds_read_b128 v[76:79], v221 offset:36960
	ds_read_b128 v[84:87], v221 offset:41568
	ds_read_b128 v[154:157], v221 offset:46176
	ds_read_b128 v[158:161], v221 offset:50784
	s_waitcnt lgkmcnt(8)
	v_mfma_f32_32x32x16_bf16 v[16:31], v[68:71], v[64:67], v[16:31]
	s_mov_b32 s27, 0xf149f2ca
	v_max3_f32 v68, v112, s27, v113
	v_max3_f32 v68, v68, v114, v115
	v_max3_f32 v68, v68, v116, v117
	v_max3_f32 v68, v68, v118, v119
	s_waitcnt lgkmcnt(7)
	v_mfma_f32_32x32x16_bf16 v[48:63], v[80:83], v[64:67], v[48:63]
	s_waitcnt lgkmcnt(6)
	v_mfma_f32_32x32x16_bf16 v[32:47], v[88:91], v[64:67], v[32:47]
	v_max3_f32 v68, v68, v120, v121
	v_max3_f32 v68, v68, v122, v123
	v_max3_f32 v68, v68, v124, v125
	v_max3_f32 v68, v68, v126, v127
	s_waitcnt lgkmcnt(5)
	v_mfma_f32_32x32x16_bf16 v[0:15], v[92:95], v[64:67], v[0:15]
	s_waitcnt vmcnt(1)
	ds_write_b128 v249, v[150:153] offset:36864
	s_waitcnt lgkmcnt(4)
	v_mfma_f32_32x32x16_bf16 v[16:31], v[76:79], v[72:75], v[16:31]
	v_max3_f32 v64, v68, v96, v97
	v_max3_f32 v64, v64, v98, v99
	v_max3_f32 v64, v64, v100, v101
	v_max3_f32 v64, v64, v102, v103
	s_waitcnt lgkmcnt(3)
	v_mfma_f32_32x32x16_bf16 v[48:63], v[84:87], v[72:75], v[48:63]
	s_waitcnt lgkmcnt(2)
	v_mfma_f32_32x32x16_bf16 v[32:47], v[154:157], v[72:75], v[32:47]
	v_max3_f32 v64, v64, v104, v105
	v_max3_f32 v64, v64, v106, v107
	v_max3_f32 v64, v64, v108, v109
	v_max3_f32 v64, v64, v110, v111
	s_waitcnt lgkmcnt(1)
	v_mfma_f32_32x32x16_bf16 v[0:15], v[158:161], v[72:75], v[0:15]
	s_waitcnt vmcnt(0)
	ds_write_b128 v248, v[146:149] offset:36864
	v_add_f32_e32 v65, v222, v223
	v_add_f32_e32 v158, v191, v65
	v_mov_b32_e32 v65, v64
	s_nop 1
	v_permlane32_swap_b32_e32 v64, v65
	v_max_f32_e32 v64, v64, v65
	v_sub_f32_e32 v65, v64, v220
	v_mul_f32_e32 v65, 0x3e38aa3b, v65
	v_cmp_lt_f32_e32 vcc, s5, v65
	s_cbranch_vccz .LBB0_260
	v_max_f32_e32 v64, v64, v64
	v_max_f32_e32 v65, v220, v220
	v_max_f32_e32 v65, v65, v64
	v_sub_f32_e32 v64, v220, v65
	v_mul_f32_e32 v64, 0x3e38aa3b, v64
	v_exp_f32_e32 v64, v64
	v_mul_f32_e32 v190, 0x3e38aa3b, v65
	v_mov_b32_e32 v220, v65
	v_pk_mul_f32 v[30:31], v[30:31], v[64:65] op_sel_hi:[1,0]
	v_pk_mul_f32 v[28:29], v[28:29], v[64:65] op_sel_hi:[1,0]
	v_pk_mul_f32 v[26:27], v[26:27], v[64:65] op_sel_hi:[1,0]
	v_pk_mul_f32 v[24:25], v[24:25], v[64:65] op_sel_hi:[1,0]
	v_pk_mul_f32 v[22:23], v[22:23], v[64:65] op_sel_hi:[1,0]
	v_pk_mul_f32 v[20:21], v[20:21], v[64:65] op_sel_hi:[1,0]
	v_pk_mul_f32 v[18:19], v[18:19], v[64:65] op_sel_hi:[1,0]
	v_pk_mul_f32 v[16:17], v[16:17], v[64:65] op_sel_hi:[1,0]
	v_pk_mul_f32 v[62:63], v[62:63], v[64:65] op_sel_hi:[1,0]
	v_pk_mul_f32 v[60:61], v[60:61], v[64:65] op_sel_hi:[1,0]
	v_pk_mul_f32 v[58:59], v[58:59], v[64:65] op_sel_hi:[1,0]
	v_pk_mul_f32 v[56:57], v[56:57], v[64:65] op_sel_hi:[1,0]
	v_pk_mul_f32 v[54:55], v[54:55], v[64:65] op_sel_hi:[1,0]
	v_pk_mul_f32 v[52:53], v[52:53], v[64:65] op_sel_hi:[1,0]
	v_pk_mul_f32 v[50:51], v[50:51], v[64:65] op_sel_hi:[1,0]
	v_pk_mul_f32 v[48:49], v[48:49], v[64:65] op_sel_hi:[1,0]
	v_pk_mul_f32 v[46:47], v[46:47], v[64:65] op_sel_hi:[1,0]
	v_pk_mul_f32 v[44:45], v[44:45], v[64:65] op_sel_hi:[1,0]
	v_pk_mul_f32 v[42:43], v[42:43], v[64:65] op_sel_hi:[1,0]
	v_pk_mul_f32 v[40:41], v[40:41], v[64:65] op_sel_hi:[1,0]
	v_pk_mul_f32 v[38:39], v[38:39], v[64:65] op_sel_hi:[1,0]
	v_pk_mul_f32 v[36:37], v[36:37], v[64:65] op_sel_hi:[1,0]
	v_pk_mul_f32 v[34:35], v[34:35], v[64:65] op_sel_hi:[1,0]
	v_pk_mul_f32 v[32:33], v[32:33], v[64:65] op_sel_hi:[1,0]
	v_pk_mul_f32 v[14:15], v[14:15], v[64:65] op_sel_hi:[1,0]
	v_pk_mul_f32 v[12:13], v[12:13], v[64:65] op_sel_hi:[1,0]
	v_pk_mul_f32 v[10:11], v[10:11], v[64:65] op_sel_hi:[1,0]
	v_pk_mul_f32 v[8:9], v[8:9], v[64:65] op_sel_hi:[1,0]
	v_pk_mul_f32 v[6:7], v[6:7], v[64:65] op_sel_hi:[1,0]
	v_pk_mul_f32 v[4:5], v[4:5], v[64:65] op_sel_hi:[1,0]
	v_pk_mul_f32 v[2:3], v[2:3], v[64:65] op_sel_hi:[1,0]
	v_pk_mul_f32 v[0:1], v[0:1], v[64:65] op_sel_hi:[1,0]
	v_mul_f32_e32 v158, v158, v64
.LBB0_260:
	v_add_co_u32_e32 v64, vcc, 0xa906000, v194
	s_waitcnt lgkmcnt(0)
	s_nop 0
	v_addc_co_u32_e32 v65, vcc, 0, v195, vcc
	s_barrier
	global_load_dwordx4 v[222:225], v[64:65], off
	v_add_co_u32_e32 v64, vcc, 0xa906000, v192
	v_mov_b32_e32 v191, v190
	s_nop 0
	v_addc_co_u32_e32 v65, vcc, 0, v193, vcc
	global_load_dwordx4 v[154:157], v[64:65], off
	global_load_dwordx4 v[150:153], v[196:197], off offset:384
	global_load_dwordx4 v[146:149], v[198:199], off offset:384
	ds_read_b128 v[64:67], v219
	ds_read_b128 v[192:195], v219 offset:32
	ds_read_b128 v[68:71], v219 offset:4608
	ds_read_b128 v[196:199], v219 offset:4640
	ds_read_b128 v[226:229], v219 offset:64
	ds_read_b128 v[230:233], v219 offset:96
	ds_read_b128 v[234:237], v219 offset:4672
	ds_read_b128 v[238:241], v219 offset:4704
	s_waitcnt lgkmcnt(7)
	v_mfma_f32_32x32x16_bf16 v[80:95], v[64:67], v[142:145], 0
	v_fma_f32 v72, v112, s78, -v190
	v_fma_f32 v73, v113, s78, -v191
	v_fma_f32 v74, v114, s78, -v190
	v_fma_f32 v75, v115, s78, -v191
	v_exp_f32_e32 v72, v72
	v_exp_f32_e32 v73, v73
	v_exp_f32_e32 v74, v74
	v_exp_f32_e32 v75, v75
	v_pk_add_f32 v[64:65], v[72:73], 0 op_sel_hi:[1,0]
	v_cvt_pk_bf16_f32 v112, v72, v73
	v_pk_add_f32 v[114:115], v[74:75], v[64:65]
	v_cvt_pk_bf16_f32 v113, v74, v75
	s_waitcnt lgkmcnt(5)
	v_mfma_f32_32x32x16_bf16 v[64:79], v[68:71], v[142:145], 0
	v_mfma_f32_32x32x16_bf16 v[80:95], v[192:195], v[136:139], v[80:95]
	v_fma_f32 v116, v116, s78, -v190
	v_fma_f32 v117, v117, s78, -v191
	v_fma_f32 v118, v118, s78, -v190
	v_fma_f32 v119, v119, s78, -v191
	v_exp_f32_e32 v116, v116
	v_exp_f32_e32 v117, v117
	v_exp_f32_e32 v118, v118
	v_exp_f32_e32 v119, v119
	v_pk_add_f32 v[114:115], v[116:117], v[114:115]
	s_nop 0
	v_pk_add_f32 v[160:161], v[118:119], v[114:115]
	v_cvt_pk_bf16_f32 v114, v116, v117
	v_cvt_pk_bf16_f32 v115, v118, v119
	s_waitcnt lgkmcnt(4)
	v_mfma_f32_32x32x16_bf16 v[64:79], v[196:199], v[136:139], v[64:79]
	s_waitcnt lgkmcnt(3)
	v_mfma_f32_32x32x16_bf16 v[80:95], v[226:229], v[132:135], v[80:95]
	v_fma_f32 v116, v120, s78, -v190
	v_fma_f32 v117, v121, s78, -v191
	v_fma_f32 v118, v122, s78, -v190
	v_fma_f32 v119, v123, s78, -v191
	v_exp_f32_e32 v116, v116
	v_exp_f32_e32 v117, v117
	v_exp_f32_e32 v118, v118
	v_exp_f32_e32 v119, v119
	v_pk_add_f32 v[120:121], v[116:117], v[160:161]
	v_cvt_pk_bf16_f32 v116, v116, v117
	v_pk_add_f32 v[120:121], v[118:119], v[120:121]
	v_cvt_pk_bf16_f32 v117, v118, v119
	s_waitcnt lgkmcnt(1)
	v_mfma_f32_32x32x16_bf16 v[64:79], v[234:237], v[132:135], v[64:79]
	v_mfma_f32_32x32x16_bf16 v[80:95], v[230:233], v[128:131], v[80:95]
	v_fma_f32 v118, v124, s78, -v190
	v_fma_f32 v119, v125, s78, -v191
	v_fma_f32 v122, v126, s78, -v190
	v_fma_f32 v123, v127, s78, -v191
	v_exp_f32_e32 v118, v118
	v_exp_f32_e32 v119, v119
	v_exp_f32_e32 v122, v122
	v_exp_f32_e32 v123, v123
	v_pk_add_f32 v[120:121], v[118:119], v[120:121]
	v_cvt_pk_bf16_f32 v118, v118, v119
	v_pk_add_f32 v[160:161], v[122:123], v[120:121]
	v_cvt_pk_bf16_f32 v119, v122, v123
	s_waitcnt lgkmcnt(0)
	v_mfma_f32_32x32x16_bf16 v[64:79], v[238:241], v[128:131], v[64:79]
	s_mulk_i32 s24, 0x4800
	v_add_u32_e32 v159, s24, v218
	ds_read_b128 v[120:123], v159 offset:36864
	ds_read_b128 v[124:127], v159 offset:41472
	ds_read_b128 v[192:195], v159 offset:46080
	ds_read_b128 v[196:199], v159 offset:50688
	s_addk_i32 s25, 0x4800
	s_cmp_lg_u32 s30, 2
	s_cselect_b32 s24, s25, 0
	s_add_i32 s24, s24, 0
	v_add_u32_e32 v221, s24, v180
	v_add_u32_e32 v242, s24, v178
	ds_read_b128 v[226:229], v159 offset:36896
	ds_read_b128 v[230:233], v159 offset:41504
	ds_read_b128 v[234:237], v159 offset:46112
	ds_read_b128 v[238:241], v159 offset:50720
	s_waitcnt lgkmcnt(7)
	v_mfma_f32_32x32x16_bf16 v[16:31], v[120:123], v[112:115], v[16:31]
	v_fma_f32 v96, v96, s78, -v190
	v_fma_f32 v97, v97, s78, -v191
	v_fma_f32 v98, v98, s78, -v190
	v_fma_f32 v99, v99, s78, -v191
	v_exp_f32_e32 v96, v96
	v_exp_f32_e32 v97, v97
	v_exp_f32_e32 v98, v98
	v_exp_f32_e32 v99, v99
	v_pk_add_f32 v[120:121], v[96:97], v[160:161]
	v_cvt_pk_bf16_f32 v96, v96, v97
	v_pk_add_f32 v[120:121], v[98:99], v[120:121]
	v_cvt_pk_bf16_f32 v97, v98, v99
	s_waitcnt lgkmcnt(6)
	v_mfma_f32_32x32x16_bf16 v[48:63], v[124:127], v[112:115], v[48:63]
	s_waitcnt lgkmcnt(5)
	v_mfma_f32_32x32x16_bf16 v[32:47], v[192:195], v[112:115], v[32:47]
	v_fma_f32 v98, v100, s78, -v190
	v_fma_f32 v99, v101, s78, -v191
	v_fma_f32 v100, v102, s78, -v190
	v_fma_f32 v101, v103, s78, -v191
	v_exp_f32_e32 v98, v98
	v_exp_f32_e32 v99, v99
	v_exp_f32_e32 v100, v100
	v_exp_f32_e32 v101, v101
	v_pk_add_f32 v[102:103], v[98:99], v[120:121]
	v_cvt_pk_bf16_f32 v98, v98, v99
	v_pk_add_f32 v[160:161], v[100:101], v[102:103]
	v_cvt_pk_bf16_f32 v99, v100, v101
	s_waitcnt lgkmcnt(4)
	v_mfma_f32_32x32x16_bf16 v[0:15], v[196:199], v[112:115], v[0:15]
	s_waitcnt vmcnt(3)
	ds_write_b128 v217, v[222:225] offset:18432
	ds_read_b128 v[100:103], v159 offset:36928
	ds_read_b128 v[112:115], v159 offset:41536
	ds_read_b128 v[120:123], v159 offset:46144
	ds_read_b128 v[124:127], v159 offset:50752
	s_waitcnt lgkmcnt(8)
	v_mfma_f32_32x32x16_bf16 v[16:31], v[226:229], v[116:119], v[16:31]
	v_fma_f32 v104, v104, s78, -v190
	v_fma_f32 v105, v105, s78, -v191
	v_fma_f32 v106, v106, s78, -v190
	v_fma_f32 v107, v107, s78, -v191
	v_exp_f32_e32 v104, v104
	v_exp_f32_e32 v105, v105
	v_exp_f32_e32 v106, v106
	v_exp_f32_e32 v107, v107
	v_pk_add_f32 v[160:161], v[104:105], v[160:161]
	v_cvt_pk_bf16_f32 v104, v104, v105
	v_pk_add_f32 v[160:161], v[106:107], v[160:161]
	v_cvt_pk_bf16_f32 v105, v106, v107
	s_waitcnt lgkmcnt(7)
	v_mfma_f32_32x32x16_bf16 v[48:63], v[230:233], v[116:119], v[48:63]
	s_waitcnt lgkmcnt(6)
	v_mfma_f32_32x32x16_bf16 v[32:47], v[234:237], v[116:119], v[32:47]
	v_fma_f32 v106, v108, s78, -v190
	v_fma_f32 v107, v109, s78, -v191
	v_fma_f32 v108, v110, s78, -v190
	v_fma_f32 v109, v111, s78, -v191
	v_exp_f32_e32 v106, v106
	v_exp_f32_e32 v107, v107
	v_exp_f32_e32 v108, v108
	v_exp_f32_e32 v109, v109
	v_pk_add_f32 v[110:111], v[106:107], v[160:161]
	v_cvt_pk_bf16_f32 v106, v106, v107
	v_pk_add_f32 v[160:161], v[108:109], v[110:111]
	v_cvt_pk_bf16_f32 v107, v108, v109
	s_waitcnt lgkmcnt(5)
	v_mfma_f32_32x32x16_bf16 v[0:15], v[238:241], v[116:119], v[0:15]
	s_waitcnt vmcnt(2)
	ds_write_b128 v216, v[154:157] offset:18432
	ds_read_b128 v[108:111], v159 offset:36960
	ds_read_b128 v[116:119], v159 offset:41568
	ds_read_b128 v[154:157], v159 offset:46176
	ds_read_b128 v[190:193], v159 offset:50784
	s_waitcnt lgkmcnt(8)
	v_mfma_f32_32x32x16_bf16 v[16:31], v[100:103], v[96:99], v[16:31]
	s_mov_b32 s24, 0xf149f2ca
	v_max3_f32 v100, v80, s24, v81
	v_max3_f32 v100, v100, v82, v83
	v_max3_f32 v100, v100, v84, v85
	v_max3_f32 v100, v100, v86, v87
	s_waitcnt lgkmcnt(7)
	v_mfma_f32_32x32x16_bf16 v[48:63], v[112:115], v[96:99], v[48:63]
	s_waitcnt lgkmcnt(6)
	v_mfma_f32_32x32x16_bf16 v[32:47], v[120:123], v[96:99], v[32:47]
	v_max3_f32 v100, v100, v88, v89
	v_max3_f32 v100, v100, v90, v91
	v_max3_f32 v100, v100, v92, v93
	v_max3_f32 v100, v100, v94, v95
	s_waitcnt lgkmcnt(5)
	v_mfma_f32_32x32x16_bf16 v[0:15], v[124:127], v[96:99], v[0:15]
	s_waitcnt vmcnt(1)
	ds_write_b128 v242, v[150:153] offset:36864
	s_waitcnt lgkmcnt(4)
	v_mfma_f32_32x32x16_bf16 v[16:31], v[108:111], v[104:107], v[16:31]
	v_max3_f32 v96, v100, v64, v65
	v_max3_f32 v96, v96, v66, v67
	v_max3_f32 v96, v96, v68, v69
	v_max3_f32 v96, v96, v70, v71
	s_waitcnt lgkmcnt(3)
	v_mfma_f32_32x32x16_bf16 v[48:63], v[116:119], v[104:107], v[48:63]
	s_waitcnt lgkmcnt(2)
	v_mfma_f32_32x32x16_bf16 v[32:47], v[154:157], v[104:107], v[32:47]
	v_max3_f32 v96, v96, v72, v73
	v_max3_f32 v96, v96, v74, v75
	v_max3_f32 v96, v96, v76, v77
	v_max3_f32 v96, v96, v78, v79
	s_waitcnt lgkmcnt(1)
	v_mfma_f32_32x32x16_bf16 v[0:15], v[190:193], v[104:107], v[0:15]
	s_waitcnt vmcnt(0)
	ds_write_b128 v221, v[146:149] offset:36864
	v_add_f32_e32 v97, v160, v161
	v_add_f32_e32 v191, v158, v97
	v_mov_b32_e32 v97, v96
	s_nop 1
	v_permlane32_swap_b32_e32 v96, v97
	v_max_f32_e32 v96, v96, v97
	v_sub_f32_e32 v97, v96, v220
	v_mul_f32_e32 v97, 0x3e38aa3b, v97
	v_cmp_lt_f32_e32 vcc, s5, v97
	s_movk_i32 s27, 0x2000
	s_cbranch_vccz .LBB0_257
	v_max_f32_e32 v96, v96, v96
	v_max_f32_e32 v97, v220, v220
	v_max_f32_e32 v97, v97, v96
	v_sub_f32_e32 v96, v220, v97
	v_mul_f32_e32 v96, 0x3e38aa3b, v96
	v_exp_f32_e32 v96, v96
	v_mov_b32_e32 v220, v97
	v_pk_mul_f32 v[30:31], v[30:31], v[96:97] op_sel_hi:[1,0]
	v_pk_mul_f32 v[28:29], v[28:29], v[96:97] op_sel_hi:[1,0]
	v_pk_mul_f32 v[26:27], v[26:27], v[96:97] op_sel_hi:[1,0]
	v_pk_mul_f32 v[24:25], v[24:25], v[96:97] op_sel_hi:[1,0]
	v_pk_mul_f32 v[22:23], v[22:23], v[96:97] op_sel_hi:[1,0]
	v_pk_mul_f32 v[20:21], v[20:21], v[96:97] op_sel_hi:[1,0]
	v_pk_mul_f32 v[18:19], v[18:19], v[96:97] op_sel_hi:[1,0]
	v_pk_mul_f32 v[16:17], v[16:17], v[96:97] op_sel_hi:[1,0]
	v_pk_mul_f32 v[62:63], v[62:63], v[96:97] op_sel_hi:[1,0]
	v_pk_mul_f32 v[60:61], v[60:61], v[96:97] op_sel_hi:[1,0]
	v_pk_mul_f32 v[58:59], v[58:59], v[96:97] op_sel_hi:[1,0]
	v_pk_mul_f32 v[56:57], v[56:57], v[96:97] op_sel_hi:[1,0]
	v_pk_mul_f32 v[54:55], v[54:55], v[96:97] op_sel_hi:[1,0]
	v_pk_mul_f32 v[52:53], v[52:53], v[96:97] op_sel_hi:[1,0]
	v_pk_mul_f32 v[50:51], v[50:51], v[96:97] op_sel_hi:[1,0]
	v_pk_mul_f32 v[48:49], v[48:49], v[96:97] op_sel_hi:[1,0]
	v_pk_mul_f32 v[46:47], v[46:47], v[96:97] op_sel_hi:[1,0]
	v_pk_mul_f32 v[44:45], v[44:45], v[96:97] op_sel_hi:[1,0]
	v_pk_mul_f32 v[42:43], v[42:43], v[96:97] op_sel_hi:[1,0]
	v_pk_mul_f32 v[40:41], v[40:41], v[96:97] op_sel_hi:[1,0]
	v_pk_mul_f32 v[38:39], v[38:39], v[96:97] op_sel_hi:[1,0]
	v_pk_mul_f32 v[36:37], v[36:37], v[96:97] op_sel_hi:[1,0]
	v_pk_mul_f32 v[34:35], v[34:35], v[96:97] op_sel_hi:[1,0]
	v_pk_mul_f32 v[32:33], v[32:33], v[96:97] op_sel_hi:[1,0]
	v_pk_mul_f32 v[14:15], v[14:15], v[96:97] op_sel_hi:[1,0]
	v_pk_mul_f32 v[12:13], v[12:13], v[96:97] op_sel_hi:[1,0]
	v_pk_mul_f32 v[10:11], v[10:11], v[96:97] op_sel_hi:[1,0]
	v_pk_mul_f32 v[8:9], v[8:9], v[96:97] op_sel_hi:[1,0]
	v_pk_mul_f32 v[6:7], v[6:7], v[96:97] op_sel_hi:[1,0]
	v_pk_mul_f32 v[4:5], v[4:5], v[96:97] op_sel_hi:[1,0]
	v_pk_mul_f32 v[2:3], v[2:3], v[96:97] op_sel_hi:[1,0]
	v_pk_mul_f32 v[0:1], v[0:1], v[96:97] op_sel_hi:[1,0]
	v_mul_f32_e32 v191, v191, v96
	s_branch .LBB0_257
